# attn FAST loop hand-rescheduled: softmax VALU interleaved into QK MFMA gaps, K frags double-buffered + prefetched, PV group0 prefetched, one barrier per tile
# speedup vs baseline: 1.0102x; 1.0102x over previous
.LBB0_431:
	ds_read_b128 v[172:175], v221 offset:49152
	ds_read_b128 v[176:179], v221 offset:57344
	ds_read_b128 v[164:167], v223 offset:49152
	ds_read_b128 v[168:171], v223 offset:57344
.Lattn_h1:
	s_waitcnt lgkmcnt(3)
	v_mfma_f32_32x32x16_bf16 v[98:113], v[172:175], v[144:147], 0
	v_exp_f32_e32 v239, v66
	v_exp_f32_e32 v240, v67
	v_add_f32_e32 v202, 0, v229
	v_add_f32_e32 v202, v230, v202
	s_waitcnt lgkmcnt(2)
	v_mfma_f32_32x32x16_bf16 v[82:97], v[176:179], v[144:147], 0
	ds_read_b128 v[172:175], v219 offset:49152
	ds_read_b128 v[176:179], v219 offset:57344
	v_exp_f32_e32 v241, v68
	v_exp_f32_e32 v242, v69
	v_add_f32_e32 v202, v231, v202
	v_add_f32_e32 v202, v233, v202
	s_waitcnt lgkmcnt(3)
	v_mfma_f32_32x32x16_bf16 v[98:113], v[164:167], v[140:143], v[98:113]
	v_exp_f32_e32 v243, v70
	v_exp_f32_e32 v244, v71
	v_add_f32_e32 v202, v234, v202
	v_add_f32_e32 v202, v236, v202
	s_waitcnt lgkmcnt(2)
	v_mfma_f32_32x32x16_bf16 v[82:97], v[168:171], v[140:143], v[82:97]
	ds_read_b128 v[164:167], v216 offset:49152
	ds_read_b128 v[168:171], v216 offset:57344
	v_exp_f32_e32 v245, v72
	v_exp_f32_e32 v246, v73
	v_add_f32_e32 v202, v232, v202
	v_add_f32_e32 v202, v235, v202
	s_waitcnt lgkmcnt(3)
	v_mfma_f32_32x32x16_bf16 v[98:113], v[172:175], v[136:139], v[98:113]
	v_cvt_pk_bf16_f32 v66, v229, v230
	v_cvt_pk_bf16_f32 v67, v231, v233
	v_cvt_pk_bf16_f32 v68, v234, v236
	v_cvt_pk_bf16_f32 v69, v232, v235
	v_add_f32_e32 v202, v199, v202
	v_add_f32_e32 v202, v200, v202
	s_waitcnt lgkmcnt(2)
	v_mfma_f32_32x32x16_bf16 v[82:97], v[176:179], v[136:139], v[82:97]
	ds_read_b128 v[172:175], v215 offset:49152
	ds_read_b128 v[176:179], v215 offset:57344
	v_add_f32_e32 v202, v201, v202
	v_add_f32_e32 v202, v227, v202
	v_permlane32_swap_b32_e32 v66, v68
	v_permlane32_swap_b32_e32 v67, v69
	v_exp_f32_e32 v247, v74
	s_waitcnt lgkmcnt(3)
	v_mfma_f32_32x32x16_bf16 v[98:113], v[164:167], v[132:135], v[98:113]
	v_cvt_pk_bf16_f32 v70, v199, v200
	v_cvt_pk_bf16_f32 v71, v201, v227
	v_cvt_pk_bf16_f32 v72, v198, v225
	v_cvt_pk_bf16_f32 v73, v226, v228
	v_add_f32_e32 v202, v198, v202
	v_add_f32_e32 v202, v225, v202
	s_waitcnt lgkmcnt(2)
	v_mfma_f32_32x32x16_bf16 v[82:97], v[168:171], v[132:135], v[82:97]
	ds_read_b128 v[164:167], v214 offset:49152
	ds_read_b128 v[168:171], v214 offset:57344
	v_add_f32_e32 v202, v226, v202
	v_add_f32_e32 v202, v228, v202
	v_permlane32_swap_b32_e32 v70, v72
	v_permlane32_swap_b32_e32 v71, v73
	v_exp_f32_e32 v248, v75
	s_waitcnt lgkmcnt(3)
	v_mfma_f32_32x32x16_bf16 v[98:113], v[172:175], v[128:131], v[98:113]
	v_exp_f32_e32 v249, v76
	v_exp_f32_e32 v250, v77
	v_add_f32_e32 v202, v239, v202
	v_add_f32_e32 v202, v240, v202
	s_waitcnt vmcnt(0)
	ds_write_b128 v220, v[156:159] offset:32768
	ds_write_b128 v222, v[160:163] offset:32768
	s_waitcnt lgkmcnt(4)
	v_mfma_f32_32x32x16_bf16 v[82:97], v[176:179], v[128:131], v[82:97]
	ds_read_b128 v[172:175], v213 offset:49152
	ds_read_b128 v[176:179], v213 offset:57344
	v_exp_f32_e32 v251, v78
	v_exp_f32_e32 v252, v79
	v_add_f32_e32 v202, v241, v202
	v_add_f32_e32 v202, v242, v202
	s_waitcnt lgkmcnt(5)
	v_mfma_f32_32x32x16_bf16 v[98:113], v[164:167], v[124:127], v[98:113]
	v_exp_f32_e32 v182, v80
	v_exp_f32_e32 v183, v81
	v_add_f32_e32 v202, v243, v202
	v_add_f32_e32 v202, v244, v202
	s_waitcnt lgkmcnt(4)
	v_mfma_f32_32x32x16_bf16 v[82:97], v[168:171], v[124:127], v[82:97]
	ds_read_b128 v[164:167], v224 offset:49152
	ds_read_b128 v[168:171], v224 offset:57344
	v_cvt_pk_bf16_f32 v74, v239, v240
	v_cvt_pk_bf16_f32 v75, v241, v242
	v_cvt_pk_bf16_f32 v76, v243, v244
	v_cvt_pk_bf16_f32 v77, v245, v246
	v_add_f32_e32 v202, v245, v202
	v_add_f32_e32 v202, v246, v202
	s_waitcnt lgkmcnt(3)
	v_mfma_f32_32x32x16_bf16 v[98:113], v[172:175], v[120:123], v[98:113]
	v_add_f32_e32 v202, v247, v202
	v_add_f32_e32 v202, v248, v202
	v_permlane32_swap_b32_e32 v74, v76
	v_permlane32_swap_b32_e32 v75, v77
	v_add_f32_e32 v202, v249, v202
	s_waitcnt lgkmcnt(2)
	v_mfma_f32_32x32x16_bf16 v[82:97], v[176:179], v[120:123], v[82:97]
	v_cvt_pk_bf16_f32 v78, v247, v248
	v_cvt_pk_bf16_f32 v79, v249, v250
	v_cvt_pk_bf16_f32 v80, v251, v252
	v_cvt_pk_bf16_f32 v81, v182, v183
	v_add_f32_e32 v202, v250, v202
	v_add_f32_e32 v202, v251, v202
	ds_read_b64_tr_b16 v[198:199], v180 offset:0
	ds_read_b64_tr_b16 v[200:201], v180 offset:2048
	s_waitcnt lgkmcnt(3)
	v_mfma_f32_32x32x16_bf16 v[98:113], v[164:167], v[116:119], v[98:113]
	v_add_f32_e32 v202, v252, v202
	v_add_f32_e32 v202, v182, v202
	v_permlane32_swap_b32_e32 v78, v80
	v_permlane32_swap_b32_e32 v79, v81
	v_add_f32_e32 v202, v183, v202
	ds_read_b64_tr_b16 v[226:227], v180 offset:4096
	ds_read_b64_tr_b16 v[228:229], v180 offset:6144
	s_waitcnt lgkmcnt(4)
	v_mfma_f32_32x32x16_bf16 v[82:97], v[168:171], v[116:119], v[82:97]
	v_mov_b32_e32 v238, v202
	ds_read_b64_tr_b16 v[230:231], v180 offset:8192
	ds_read_b64_tr_b16 v[232:233], v180 offset:10240
	ds_read_b64_tr_b16 v[234:235], v180 offset:12288
	ds_read_b64_tr_b16 v[236:237], v180 offset:14336
	v_permlane32_swap_b32_e32 v202, v238
	v_add_f32_e32 v238, v202, v238
	v_add_f32_e32 v1, v1, v238
	s_waitcnt lgkmcnt(6)
	v_mfma_f32_32x32x16_bf16 v[2:17], v[66:69], v[198:201], v[2:17]
	ds_read_b64_tr_b16 v[198:199], v180 offset:512
	ds_read_b64_tr_b16 v[200:201], v180 offset:2560
	v_exp_f32_e32 v239, v98
	v_lshl_add_u64 v[188:189], v[196:197], 0, s[48:49]
	v_lshl_add_u64 v[186:187], v[194:195], 0, s[48:49]
	s_waitcnt lgkmcnt(6)
	v_mfma_f32_32x32x16_bf16 v[2:17], v[70:73], v[226:229], v[2:17]
	ds_read_b64_tr_b16 v[226:227], v180 offset:4608
	ds_read_b64_tr_b16 v[228:229], v180 offset:6656
	v_exp_f32_e32 v240, v99
	v_add_co_u32_e32 v164, vcc, s62, v188
	s_mov_b32 s3, 0x5f238000
	s_waitcnt lgkmcnt(6)
	v_mfma_f32_32x32x16_bf16 v[2:17], v[74:77], v[230:233], v[2:17]
	ds_read_b64_tr_b16 v[230:231], v180 offset:8704
	ds_read_b64_tr_b16 v[232:233], v180 offset:10752
	v_exp_f32_e32 v241, v100
	v_addc_co_u32_e32 v165, vcc, 0, v189, vcc
	v_add_co_u32_e32 v168, vcc, s59, v188
	s_waitcnt lgkmcnt(6)
	v_mfma_f32_32x32x16_bf16 v[2:17], v[78:81], v[234:237], v[2:17]
	ds_read_b64_tr_b16 v[234:235], v180 offset:12800
	ds_read_b64_tr_b16 v[236:237], v180 offset:14848
	v_exp_f32_e32 v242, v101
	global_load_dwordx4 v[164:167], v[164:165], off offset:1024
	v_addc_co_u32_e32 v169, vcc, 0, v189, vcc
	v_add_co_u32_e32 v172, vcc, s24, v186
	s_waitcnt lgkmcnt(6)
	v_mfma_f32_32x32x16_bf16 v[18:33], v[66:69], v[198:201], v[18:33]
	ds_read_b64_tr_b16 v[198:199], v180 offset:1024
	ds_read_b64_tr_b16 v[200:201], v180 offset:3072
	v_exp_f32_e32 v243, v102
	global_load_dwordx4 v[168:171], v[168:169], off offset:1024
	v_addc_co_u32_e32 v173, vcc, 0, v187, vcc
	v_add_co_u32_e32 v176, vcc, s3, v186
	s_waitcnt lgkmcnt(6)
	v_mfma_f32_32x32x16_bf16 v[18:33], v[70:73], v[226:229], v[18:33]
	ds_read_b64_tr_b16 v[226:227], v180 offset:5120
	ds_read_b64_tr_b16 v[228:229], v180 offset:7168
	v_exp_f32_e32 v244, v103
	global_load_dwordx4 v[172:175], v[172:173], off
	v_addc_co_u32_e32 v177, vcc, 0, v187, vcc
	s_waitcnt lgkmcnt(6)
	v_mfma_f32_32x32x16_bf16 v[18:33], v[74:77], v[230:233], v[18:33]
	ds_read_b64_tr_b16 v[230:231], v180 offset:9216
	ds_read_b64_tr_b16 v[232:233], v180 offset:11264
	v_exp_f32_e32 v245, v104
	v_exp_f32_e32 v246, v105
	global_load_dwordx4 v[176:179], v[176:177], off
	s_waitcnt lgkmcnt(6)
	v_mfma_f32_32x32x16_bf16 v[18:33], v[78:81], v[234:237], v[18:33]
	ds_read_b64_tr_b16 v[234:235], v180 offset:13312
	ds_read_b64_tr_b16 v[236:237], v180 offset:15360
	v_exp_f32_e32 v247, v106
	v_exp_f32_e32 v248, v107
	s_waitcnt lgkmcnt(6)
	v_mfma_f32_32x32x16_bf16 v[34:49], v[66:69], v[198:201], v[34:49]
	ds_read_b64_tr_b16 v[198:199], v180 offset:1536
	ds_read_b64_tr_b16 v[200:201], v180 offset:3584
	v_exp_f32_e32 v249, v108
	v_exp_f32_e32 v250, v109
	s_waitcnt lgkmcnt(6)
	v_mfma_f32_32x32x16_bf16 v[34:49], v[70:73], v[226:229], v[34:49]
	ds_read_b64_tr_b16 v[226:227], v180 offset:5632
	ds_read_b64_tr_b16 v[228:229], v180 offset:7680
	v_exp_f32_e32 v251, v110
	v_exp_f32_e32 v252, v111
	s_waitcnt lgkmcnt(6)
	v_mfma_f32_32x32x16_bf16 v[34:49], v[74:77], v[230:233], v[34:49]
	ds_read_b64_tr_b16 v[230:231], v180 offset:9728
	ds_read_b64_tr_b16 v[232:233], v180 offset:11776
	v_exp_f32_e32 v182, v112
	v_exp_f32_e32 v183, v113
	s_waitcnt lgkmcnt(6)
	v_mfma_f32_32x32x16_bf16 v[34:49], v[78:81], v[234:237], v[34:49]
	ds_read_b64_tr_b16 v[234:235], v180 offset:13824
	ds_read_b64_tr_b16 v[236:237], v180 offset:15872
	s_waitcnt lgkmcnt(0)
	v_mfma_f32_32x32x16_bf16 v[50:65], v[66:69], v[198:201], v[50:65]
	s_barrier
	ds_write_b128 v217, v[148:151] offset:0
	ds_write_b128 v218, v[152:155] offset:0
	ds_read_b128 v[156:159], v221 offset:32768
	ds_read_b128 v[160:163], v221 offset:40960
	v_mfma_f32_32x32x16_bf16 v[50:65], v[70:73], v[226:229], v[50:65]
	ds_read_b128 v[148:151], v223 offset:32768
	ds_read_b128 v[152:155], v223 offset:40960
	v_mfma_f32_32x32x16_bf16 v[50:65], v[74:77], v[230:233], v[50:65]
	v_mfma_f32_32x32x16_bf16 v[50:65], v[78:81], v[234:237], v[50:65]
	s_waitcnt lgkmcnt(3)
	v_mfma_f32_32x32x16_bf16 v[98:113], v[156:159], v[144:147], 0
	v_exp_f32_e32 v229, v82
	v_exp_f32_e32 v230, v83
	v_add_f32_e32 v202, 0, v239
	v_add_f32_e32 v202, v240, v202
	s_waitcnt lgkmcnt(2)
	v_mfma_f32_32x32x16_bf16 v[66:81], v[160:163], v[144:147], 0
	ds_read_b128 v[156:159], v219 offset:32768
	ds_read_b128 v[160:163], v219 offset:40960
	v_exp_f32_e32 v231, v84
	v_exp_f32_e32 v233, v85
	v_add_f32_e32 v202, v241, v202
	v_add_f32_e32 v202, v242, v202
	s_waitcnt lgkmcnt(3)
	v_mfma_f32_32x32x16_bf16 v[98:113], v[148:151], v[140:143], v[98:113]
	v_exp_f32_e32 v234, v86
	v_exp_f32_e32 v236, v87
	v_add_f32_e32 v202, v243, v202
	v_add_f32_e32 v202, v244, v202
	s_waitcnt lgkmcnt(2)
	v_mfma_f32_32x32x16_bf16 v[66:81], v[152:155], v[140:143], v[66:81]
	ds_read_b128 v[148:151], v216 offset:32768
	ds_read_b128 v[152:155], v216 offset:40960
	v_exp_f32_e32 v232, v88
	v_exp_f32_e32 v235, v89
	v_add_f32_e32 v202, v245, v202
	v_add_f32_e32 v202, v246, v202
	s_waitcnt lgkmcnt(3)
	v_mfma_f32_32x32x16_bf16 v[98:113], v[156:159], v[136:139], v[98:113]
	v_cvt_pk_bf16_f32 v82, v239, v240
	v_cvt_pk_bf16_f32 v83, v241, v242
	v_cvt_pk_bf16_f32 v84, v243, v244
	v_cvt_pk_bf16_f32 v85, v245, v246
	v_add_f32_e32 v202, v247, v202
	v_add_f32_e32 v202, v248, v202
	s_waitcnt lgkmcnt(2)
	v_mfma_f32_32x32x16_bf16 v[66:81], v[160:163], v[136:139], v[66:81]
	ds_read_b128 v[156:159], v215 offset:32768
	ds_read_b128 v[160:163], v215 offset:40960
	v_add_f32_e32 v202, v249, v202
	v_add_f32_e32 v202, v250, v202
	v_permlane32_swap_b32_e32 v82, v84
	v_permlane32_swap_b32_e32 v83, v85
	v_exp_f32_e32 v199, v90
	s_waitcnt lgkmcnt(3)
	v_mfma_f32_32x32x16_bf16 v[98:113], v[148:151], v[132:135], v[98:113]
	v_cvt_pk_bf16_f32 v86, v247, v248
	v_cvt_pk_bf16_f32 v87, v249, v250
	v_cvt_pk_bf16_f32 v88, v251, v252
	v_cvt_pk_bf16_f32 v89, v182, v183
	v_add_f32_e32 v202, v251, v202
	v_add_f32_e32 v202, v252, v202
	s_waitcnt lgkmcnt(2)
	v_mfma_f32_32x32x16_bf16 v[66:81], v[152:155], v[132:135], v[66:81]
	ds_read_b128 v[148:151], v214 offset:32768
	ds_read_b128 v[152:155], v214 offset:40960
	v_add_f32_e32 v202, v182, v202
	v_add_f32_e32 v202, v183, v202
	v_permlane32_swap_b32_e32 v86, v88
	v_permlane32_swap_b32_e32 v87, v89
	v_exp_f32_e32 v200, v91
	s_waitcnt lgkmcnt(3)
	v_mfma_f32_32x32x16_bf16 v[98:113], v[156:159], v[128:131], v[98:113]
	v_exp_f32_e32 v201, v92
	v_exp_f32_e32 v227, v93
	v_add_f32_e32 v202, v229, v202
	v_add_f32_e32 v202, v230, v202
	s_waitcnt vmcnt(0)
	ds_write_b128 v220, v[172:175] offset:49152
	ds_write_b128 v222, v[176:179] offset:49152
	s_waitcnt lgkmcnt(4)
	v_mfma_f32_32x32x16_bf16 v[66:81], v[160:163], v[128:131], v[66:81]
	ds_read_b128 v[156:159], v213 offset:32768
	ds_read_b128 v[160:163], v213 offset:40960
	v_exp_f32_e32 v198, v94
	v_exp_f32_e32 v225, v95
	v_add_f32_e32 v202, v231, v202
	v_add_f32_e32 v202, v233, v202
	s_waitcnt lgkmcnt(5)
	v_mfma_f32_32x32x16_bf16 v[98:113], v[148:151], v[124:127], v[98:113]
	v_exp_f32_e32 v226, v96
	v_exp_f32_e32 v228, v97
	v_add_f32_e32 v202, v234, v202
	v_add_f32_e32 v202, v236, v202
	s_waitcnt lgkmcnt(4)
	v_mfma_f32_32x32x16_bf16 v[66:81], v[152:155], v[124:127], v[66:81]
	ds_read_b128 v[148:151], v224 offset:32768
	ds_read_b128 v[152:155], v224 offset:40960
	v_cvt_pk_bf16_f32 v90, v229, v230
	v_cvt_pk_bf16_f32 v91, v231, v233
	v_cvt_pk_bf16_f32 v92, v234, v236
	v_cvt_pk_bf16_f32 v93, v232, v235
	v_add_f32_e32 v202, v232, v202
	v_add_f32_e32 v202, v235, v202
	s_waitcnt lgkmcnt(3)
	v_mfma_f32_32x32x16_bf16 v[98:113], v[156:159], v[120:123], v[98:113]
	v_add_f32_e32 v202, v199, v202
	v_add_f32_e32 v202, v200, v202
	v_permlane32_swap_b32_e32 v90, v92
	v_permlane32_swap_b32_e32 v91, v93
	v_add_f32_e32 v202, v201, v202
	s_waitcnt lgkmcnt(2)
	v_mfma_f32_32x32x16_bf16 v[66:81], v[160:163], v[120:123], v[66:81]
	v_cvt_pk_bf16_f32 v94, v199, v200
	v_cvt_pk_bf16_f32 v95, v201, v227
	v_cvt_pk_bf16_f32 v96, v198, v225
	v_cvt_pk_bf16_f32 v97, v226, v228
	v_add_f32_e32 v202, v227, v202
	v_add_f32_e32 v202, v198, v202
	ds_read_b64_tr_b16 v[240:241], v115 offset:0
	ds_read_b64_tr_b16 v[242:243], v115 offset:2048
	s_waitcnt lgkmcnt(3)
	v_mfma_f32_32x32x16_bf16 v[98:113], v[148:151], v[116:119], v[98:113]
	v_add_f32_e32 v202, v225, v202
	v_add_f32_e32 v202, v226, v202
	v_permlane32_swap_b32_e32 v94, v96
	v_permlane32_swap_b32_e32 v95, v97
	v_add_f32_e32 v202, v228, v202
	ds_read_b64_tr_b16 v[244:245], v115 offset:4096
	ds_read_b64_tr_b16 v[246:247], v115 offset:6144
	s_waitcnt lgkmcnt(4)
	v_mfma_f32_32x32x16_bf16 v[66:81], v[152:155], v[116:119], v[66:81]
	v_mov_b32_e32 v238, v202
	ds_read_b64_tr_b16 v[248:249], v115 offset:8192
	ds_read_b64_tr_b16 v[250:251], v115 offset:10240
	ds_read_b64_tr_b16 v[190:191], v115 offset:12288
	ds_read_b64_tr_b16 v[192:193], v115 offset:14336
	v_permlane32_swap_b32_e32 v202, v238
	v_add_f32_e32 v238, v202, v238
	v_add_f32_e32 v1, v1, v238
	s_cmpk_gt_u32 s8, 0x7c
	s_cbranch_scc1 .Lattn_h2c_last
	s_waitcnt lgkmcnt(6)
	v_mfma_f32_32x32x16_bf16 v[2:17], v[82:85], v[240:243], v[2:17]
	ds_read_b64_tr_b16 v[240:241], v115 offset:512
	ds_read_b64_tr_b16 v[242:243], v115 offset:2560
	v_exp_f32_e32 v229, v98
	v_add_co_u32_e32 v148, vcc, 0x4d684000, v188
	s_waitcnt lgkmcnt(6)
	v_mfma_f32_32x32x16_bf16 v[2:17], v[86:89], v[244:247], v[2:17]
	ds_read_b64_tr_b16 v[244:245], v115 offset:4608
	ds_read_b64_tr_b16 v[246:247], v115 offset:6656
	v_exp_f32_e32 v230, v99
	v_addc_co_u32_e32 v149, vcc, 0, v189, vcc
	v_add_co_u32_e32 v152, vcc, 0x4d714000, v188
	s_waitcnt lgkmcnt(6)
	v_mfma_f32_32x32x16_bf16 v[2:17], v[90:93], v[248:251], v[2:17]
	ds_read_b64_tr_b16 v[248:249], v115 offset:8704
	ds_read_b64_tr_b16 v[250:251], v115 offset:10752
	v_exp_f32_e32 v231, v100
	global_load_dwordx4 v[148:151], v[148:149], off offset:1024
	v_addc_co_u32_e32 v153, vcc, 0, v189, vcc
	v_add_co_u32_e32 v156, vcc, 0x5f240000, v186
	s_waitcnt lgkmcnt(6)
	v_mfma_f32_32x32x16_bf16 v[2:17], v[94:97], v[190:193], v[2:17]
	ds_read_b64_tr_b16 v[190:191], v115 offset:12800
	ds_read_b64_tr_b16 v[192:193], v115 offset:14848
	v_exp_f32_e32 v233, v101
	global_load_dwordx4 v[152:155], v[152:153], off offset:1024
	v_addc_co_u32_e32 v157, vcc, 0, v187, vcc
	v_add_co_u32_e32 v160, vcc, 0x5f248000, v186
	s_waitcnt lgkmcnt(6)
	v_mfma_f32_32x32x16_bf16 v[18:33], v[82:85], v[240:243], v[18:33]
	ds_read_b64_tr_b16 v[240:241], v115 offset:1024
	ds_read_b64_tr_b16 v[242:243], v115 offset:3072
	v_exp_f32_e32 v234, v102
	global_load_dwordx4 v[156:159], v[156:157], off
	v_addc_co_u32_e32 v161, vcc, 0, v187, vcc
	s_waitcnt lgkmcnt(6)
	v_mfma_f32_32x32x16_bf16 v[18:33], v[86:89], v[244:247], v[18:33]
	ds_read_b64_tr_b16 v[244:245], v115 offset:5120
	ds_read_b64_tr_b16 v[246:247], v115 offset:7168
	v_exp_f32_e32 v236, v103
	global_load_dwordx4 v[160:163], v[160:161], off
	s_waitcnt lgkmcnt(6)
	v_mfma_f32_32x32x16_bf16 v[18:33], v[90:93], v[248:251], v[18:33]
	ds_read_b64_tr_b16 v[248:249], v115 offset:9216
	ds_read_b64_tr_b16 v[250:251], v115 offset:11264
	v_exp_f32_e32 v232, v104
	v_exp_f32_e32 v235, v105
	s_waitcnt lgkmcnt(6)
	v_mfma_f32_32x32x16_bf16 v[18:33], v[94:97], v[190:193], v[18:33]
	ds_read_b64_tr_b16 v[190:191], v115 offset:13312
	ds_read_b64_tr_b16 v[192:193], v115 offset:15360
	v_exp_f32_e32 v199, v106
	v_exp_f32_e32 v200, v107
	s_waitcnt lgkmcnt(6)
	v_mfma_f32_32x32x16_bf16 v[34:49], v[82:85], v[240:243], v[34:49]
	ds_read_b64_tr_b16 v[240:241], v115 offset:1536
	ds_read_b64_tr_b16 v[242:243], v115 offset:3584
	v_exp_f32_e32 v201, v108
	v_exp_f32_e32 v227, v109
	s_waitcnt lgkmcnt(6)
	v_mfma_f32_32x32x16_bf16 v[34:49], v[86:89], v[244:247], v[34:49]
	ds_read_b64_tr_b16 v[244:245], v115 offset:5632
	ds_read_b64_tr_b16 v[246:247], v115 offset:7680
	v_exp_f32_e32 v198, v110
	v_exp_f32_e32 v225, v111
	s_waitcnt lgkmcnt(6)
	v_mfma_f32_32x32x16_bf16 v[34:49], v[90:93], v[248:251], v[34:49]
	ds_read_b64_tr_b16 v[248:249], v115 offset:9728
	ds_read_b64_tr_b16 v[250:251], v115 offset:11776
	v_exp_f32_e32 v226, v112
	v_exp_f32_e32 v228, v113
	s_waitcnt lgkmcnt(6)
	v_mfma_f32_32x32x16_bf16 v[34:49], v[94:97], v[190:193], v[34:49]
	ds_read_b64_tr_b16 v[190:191], v115 offset:13824
	ds_read_b64_tr_b16 v[192:193], v115 offset:15872
	s_waitcnt lgkmcnt(0)
	v_mfma_f32_32x32x16_bf16 v[50:65], v[82:85], v[240:243], v[50:65]
	s_barrier
	ds_write_b128 v217, v[164:167] offset:16384
	ds_write_b128 v218, v[168:171] offset:16384
	ds_read_b128 v[172:175], v221 offset:49152
	ds_read_b128 v[176:179], v221 offset:57344
	v_mfma_f32_32x32x16_bf16 v[50:65], v[86:89], v[244:247], v[50:65]
	ds_read_b128 v[164:167], v223 offset:49152
	ds_read_b128 v[168:171], v223 offset:57344
	v_mfma_f32_32x32x16_bf16 v[50:65], v[90:93], v[248:251], v[50:65]
	v_mfma_f32_32x32x16_bf16 v[50:65], v[94:97], v[190:193], v[50:65]
	v_lshl_add_u64 v[194:195], v[194:195], 0, s[30:31]
	v_lshl_add_u64 v[196:197], v[196:197], 0, s[80:81]
	s_add_i32 s8, s8, 2
	s_branch .Lattn_h1
.Lattn_h2c_last:
	s_waitcnt lgkmcnt(6)
	v_mfma_f32_32x32x16_bf16 v[2:17], v[82:85], v[240:243], v[2:17]
	ds_read_b64_tr_b16 v[240:241], v115 offset:512
	ds_read_b64_tr_b16 v[242:243], v115 offset:2560
	v_exp_f32_e32 v229, v98
	s_waitcnt lgkmcnt(6)
	v_mfma_f32_32x32x16_bf16 v[2:17], v[86:89], v[244:247], v[2:17]
	ds_read_b64_tr_b16 v[244:245], v115 offset:4608
	ds_read_b64_tr_b16 v[246:247], v115 offset:6656
	v_exp_f32_e32 v230, v99
	s_waitcnt lgkmcnt(6)
	v_mfma_f32_32x32x16_bf16 v[2:17], v[90:93], v[248:251], v[2:17]
	ds_read_b64_tr_b16 v[248:249], v115 offset:8704
	ds_read_b64_tr_b16 v[250:251], v115 offset:10752
	v_exp_f32_e32 v231, v100
	s_waitcnt lgkmcnt(6)
	v_mfma_f32_32x32x16_bf16 v[2:17], v[94:97], v[190:193], v[2:17]
	ds_read_b64_tr_b16 v[190:191], v115 offset:12800
	ds_read_b64_tr_b16 v[192:193], v115 offset:14848
	v_exp_f32_e32 v233, v101
	s_waitcnt lgkmcnt(6)
	v_mfma_f32_32x32x16_bf16 v[18:33], v[82:85], v[240:243], v[18:33]
	ds_read_b64_tr_b16 v[240:241], v115 offset:1024
	ds_read_b64_tr_b16 v[242:243], v115 offset:3072
	v_exp_f32_e32 v234, v102
	s_waitcnt lgkmcnt(6)
	v_mfma_f32_32x32x16_bf16 v[18:33], v[86:89], v[244:247], v[18:33]
	ds_read_b64_tr_b16 v[244:245], v115 offset:5120
	ds_read_b64_tr_b16 v[246:247], v115 offset:7168
	v_exp_f32_e32 v236, v103
	s_waitcnt lgkmcnt(6)
	v_mfma_f32_32x32x16_bf16 v[18:33], v[90:93], v[248:251], v[18:33]
	ds_read_b64_tr_b16 v[248:249], v115 offset:9216
	ds_read_b64_tr_b16 v[250:251], v115 offset:11264
	v_exp_f32_e32 v232, v104
	v_exp_f32_e32 v235, v105
	s_waitcnt lgkmcnt(6)
	v_mfma_f32_32x32x16_bf16 v[18:33], v[94:97], v[190:193], v[18:33]
	ds_read_b64_tr_b16 v[190:191], v115 offset:13312
	ds_read_b64_tr_b16 v[192:193], v115 offset:15360
	v_exp_f32_e32 v199, v106
	v_exp_f32_e32 v200, v107
	s_waitcnt lgkmcnt(6)
	v_mfma_f32_32x32x16_bf16 v[34:49], v[82:85], v[240:243], v[34:49]
	ds_read_b64_tr_b16 v[240:241], v115 offset:1536
	ds_read_b64_tr_b16 v[242:243], v115 offset:3584
	v_exp_f32_e32 v201, v108
	v_exp_f32_e32 v227, v109
	s_waitcnt lgkmcnt(6)
	v_mfma_f32_32x32x16_bf16 v[34:49], v[86:89], v[244:247], v[34:49]
	ds_read_b64_tr_b16 v[244:245], v115 offset:5632
	ds_read_b64_tr_b16 v[246:247], v115 offset:7680
	v_exp_f32_e32 v198, v110
	v_exp_f32_e32 v225, v111
	s_waitcnt lgkmcnt(6)
	v_mfma_f32_32x32x16_bf16 v[34:49], v[90:93], v[248:251], v[34:49]
	ds_read_b64_tr_b16 v[248:249], v115 offset:9728
	ds_read_b64_tr_b16 v[250:251], v115 offset:11776
	v_exp_f32_e32 v226, v112
	v_exp_f32_e32 v228, v113
	s_waitcnt lgkmcnt(6)
	v_mfma_f32_32x32x16_bf16 v[34:49], v[94:97], v[190:193], v[34:49]
	ds_read_b64_tr_b16 v[190:191], v115 offset:13824
	ds_read_b64_tr_b16 v[192:193], v115 offset:15872
	s_waitcnt lgkmcnt(0)
	v_mfma_f32_32x32x16_bf16 v[50:65], v[82:85], v[240:243], v[50:65]
	s_barrier
	ds_write_b128 v217, v[164:167] offset:16384
	ds_write_b128 v218, v[168:171] offset:16384
	v_mfma_f32_32x32x16_bf16 v[50:65], v[86:89], v[244:247], v[50:65]
	v_mfma_f32_32x32x16_bf16 v[50:65], v[90:93], v[248:251], v[50:65]
	v_mfma_f32_32x32x16_bf16 v[50:65], v[94:97], v[190:193], v[50:65]
	v_mov_b64_e32 v[186:187], 0x400
	v_mov_b64_e32 v[188:189], 0x3ff
	v_mov_b64_e32 v[190:191], 0x1000
	v_mov_b64_e32 v[192:193], 0xfff
